# move the W_branch_a, W_branch_b, W_out weight conversions from the FFN1-in GEMM tail into the idle tail slot of the QKV GEMM phase
# speedup vs baseline: 1.0035x; 1.0020x over previous
; __global__ void __launch_bounds__(512, 2) mk_fwd(Args args) {
;     ...
;                 transpose_loop2<0, false>(args.in[11], 1024, DM, WA, nullptr, scr, first, I_A, stride, lane);
;                 transpose_loop2<0, false>(args.in[12], 1024, DM, WB, nullptr, scr, first, I_A, stride, lane);
;                 transpose_loop2<0, false>(args.in[13], DM, DM, WOUT, nullptr, scr, first, I_O, stride, lane);
;             }
;             __syncthreads();
.LBB0_151:
.LBB0_171:
	s_waitcnt lgkmcnt(0)
	s_barrier

; #define LAS __attribute__((address_space(3)))
; __global__ void __launch_bounds__(512, 2) mk_fwd(Args args) {
;     ...
;             const int rounds = (NU + G - 1) / G, n_full = NU - (rounds - 1) * G;
;             const int nh = (n_full < G) ? G - n_full : G, hidx = (n_full < G) ? bx - n_full : bx;
;             if (hidx >= 0) {
;                 LAS float* scr = (LAS float*)(ldsl + wave * 16384);
;                 constexpr int I_1B = (FF / 64) * (DM / 32), I_IN = (DM / 64) * (NIN / 32), I_A = (1024 / 64) * (DM / 32), I_O = (DM / 64) * (DM / 32);
;                 constexpr int NLATE = I_1B + I_IN + 2 * I_A + I_O;
;                 const int first = hidx * 8 + wave, stride = nh * 8;
;                 transpose_loop2<0, false>(args.in[4], FF, DM, W1B, nullptr, scr, first, I_1B, stride, lane);
;                 quant_loop2<0, true>(args.in[6], DM, NIN, (unsigned char*)WIN, args.in[5], colmax, swinv, scr, first, I_IN, stride, lane);
;                 transpose_loop2<0, false>(args.in[11], 1024, DM, WA, nullptr, scr, first, I_A, stride, lane);
.LBB0_391:
	s_sub_i32 s0, s61, 0xc0
	s_cmp_lt_i32 s0, 0
	s_cbranch_scc1 .Ltail4_done
	v_readlane_b32 s2, v239, 0
	v_readlane_b32 s3, v239, 1
	s_nop 4
	s_sub_u32 s2, s2, 0xa8
	s_subb_u32 s3, s3, 0
	s_load_dwordx2 s[78:79], s[2:3], 0x58
	s_load_dwordx4 s[80:83], s[2:3], 0x60
	s_movk_i32 s16, 0x40
	s_lshl_b32 s1, s52, 14
	s_lshl_b32 s0, s0, 3
	s_add_i32 s17, s1, 0
	s_add_i32 s14, s0, s52
	s_lshl_b32 s15, s16, 3
	s_waitcnt lgkmcnt(0)
	s_cmpk_gt_i32 s14, 0x3ff
	s_cbranch_scc1 .Lt4_164
	v_lshrrev_b32_e32 v8, 5, v176
	v_and_b32_e32 v0, 31, v177
	v_lshlrev_b32_e32 v6, 2, v0
	v_mul_u32_u24_e32 v1, 0x84, v8
	v_add3_u32 v9, s17, v6, v1
	v_lshlrev_b32_e32 v1, 3, v177
	v_mov_b32_e32 v7, 0
	v_lshrrev_b32_e32 v10, 3, v176
	v_and_b32_e32 v2, 56, v1
	v_readlane_b32 s0, v239, 40
	s_waitcnt lgkmcnt(0)
	v_lshl_add_u64 v[4:5], s[78:79], 0, v[6:7]
	v_mul_u32_u24_e32 v1, 0x84, v2
	v_lshlrev_b32_e32 v6, 1, v2
	v_readlane_b32 s1, v239, 41
	v_lshlrev_b32_e32 v3, 2, v10
	s_lshl_b32 s7, s14, 5
	v_lshl_add_u64 v[6:7], s[0:1], 0, v[6:7]
	v_add3_u32 v11, s17, v1, v3
	v_or_b32_e32 v12, 8, v10
	v_or_b32_e32 v13, 16, v10
	v_or_b32_e32 v14, 24, v10
	s_lshl_b32 s6, s16, 4
	s_lshl_b32 s12, s16, 9
	s_mov_b32 s13, s7
	s_mov_b32 s18, s14
	s_branch .Lt4_154

; #define LAS __attribute__((address_space(3)))
; __device__ __forceinline__ unsigned cvt_pk_bf16(float lo, float hi) { unsigned r; asm volatile("v_cvt_pk_bf16_f32 %0, %1, %2" : "=v"(r) : "v"(lo), "v"(hi)); return r; }
; __device__ __forceinline__ int item_d0(int n0, int mode) { if (mode != 1) return n0; const int up = n0 >= FF, jj = up ? n0 - FF : n0; return (jj >> 7) * 256 + up * 128 + (jj & 127); }
; template <int MODE>
; __device__ __forceinline__ void transpose_finish(const float (&r)[32], int K, int N, bf16_t* WT, LAS float* scr, int item, int lane) {
;     const int nblk = N / 32, kb = item / nblk, nb = item % nblk, k0 = 64 * kb, d0 = item_d0(32 * nb, MODE);
; #pragma unroll
;     for (int i = 0; i < 32; ++i) { const int kk = 2 * i + (lane >> 5); scr[kk * 33 + (lane & 31)] = r[i]; }
;     asm volatile("s_waitcnt lgkmcnt(0)" ::: "memory");
;     const int c = lane & 7;
; #pragma unroll
;     for (int j = 0; j < 4; ++j) { const int n = (lane >> 3) + 8 * j; const LAS float* sp = scr + (8 * c) * 33 + n;
;         u32x4 o; o.x = cvt_pk_bf16(sp[0 * 33], sp[1 * 33]); o.y = cvt_pk_bf16(sp[2 * 33], sp[3 * 33]); o.z = cvt_pk_bf16(sp[4 * 33], sp[5 * 33]); o.w = cvt_pk_bf16(sp[6 * 33], sp[7 * 33]);
;         *(u32x4*)(WT + (size_t)(d0 + n) * K + k0 + 8 * c) = o; }
;     asm volatile("s_waitcnt lgkmcnt(0)" ::: "memory");
; }
.Lt4_169:
	s_waitcnt vmcnt(30)
	ds_write2_b32 v10, v43, v44 offset1:66
	s_waitcnt vmcnt(28)
	ds_write2_b32 v10, v45, v47 offset0:132 offset1:198
	v_add_u32_e32 v43, 0x400, v10
	s_waitcnt vmcnt(26)
	ds_write2_b32 v43, v46, v48 offset0:8 offset1:74
	s_waitcnt vmcnt(24)
	ds_write2_b32 v43, v49, v50 offset0:140 offset1:206
	v_add_u32_e32 v44, 0x800, v10
	v_add_u32_e32 v45, 0xc00, v10
	v_add_u32_e32 v46, 0x1000, v10
	v_add_u32_e32 v47, 0x1400, v10
	v_add_u32_e32 v48, 0x1800, v10
	v_add_u32_e32 v49, 0x1c00, v10
	s_waitcnt vmcnt(22)
	ds_write2_b32 v44, v51, v52 offset0:16 offset1:82
	s_waitcnt vmcnt(20)
	ds_write2_b32 v44, v53, v55 offset0:148 offset1:214
	s_waitcnt vmcnt(18)
	ds_write2_b32 v45, v54, v56 offset0:24 offset1:90
	s_waitcnt vmcnt(16)
	ds_write2_b32 v45, v57, v58 offset0:156 offset1:222
	s_waitcnt vmcnt(14)
	ds_write2_b32 v46, v59, v60 offset0:32 offset1:98
	s_waitcnt vmcnt(12)
	ds_write2_b32 v46, v61, v63 offset0:164 offset1:230
	s_waitcnt vmcnt(10)
	ds_write2_b32 v47, v62, v64 offset0:40 offset1:106
	s_waitcnt vmcnt(8)
	ds_write2_b32 v47, v65, v66 offset0:172 offset1:238
	s_waitcnt vmcnt(6)
	ds_write2_b32 v48, v67, v68 offset0:48 offset1:114
	s_waitcnt vmcnt(4)
	ds_write2_b32 v48, v69, v71 offset0:180 offset1:246
	s_waitcnt vmcnt(2)
	ds_write2_b32 v49, v70, v72 offset0:56 offset1:122
	s_waitcnt vmcnt(0)
	ds_write2_b32 v49, v73, v74 offset0:188 offset1:254
	s_waitcnt lgkmcnt(0)
	ds_read2_b32 v[50:51], v6 offset1:33
	s_waitcnt lgkmcnt(0)
	v_cvt_pk_bf16_f32 v50, v50, v51
	ds_read2_b32 v[52:53], v6 offset0:66 offset1:99
	s_waitcnt lgkmcnt(0)
	v_cvt_pk_bf16_f32 v51, v52, v53
	ds_read2_b32 v[52:53], v6 offset0:132 offset1:165
	s_sub_i32 s16, 0, s1
	s_waitcnt lgkmcnt(0)
	v_cvt_pk_bf16_f32 v52, v52, v53
	ds_read2_b32 v[54:55], v6 offset0:198 offset1:231
	s_add_i32 s16, s16, s7
	s_waitcnt lgkmcnt(0)
	v_cvt_pk_bf16_f32 v53, v54, v55
	v_add_u32_e32 v54, s16, v5
	s_ashr_i32 s1, s0, 31
	v_ashrrev_i32_e32 v55, 31, v54
	v_lshl_add_u64 v[56:57], s[0:1], 1, v[2:3]
	v_lshlrev_b64 v[60:61], 12, v[54:55]
	v_lshl_add_u64 v[60:61], v[56:57], 0, v[60:61]
	ds_read2_b32 v[58:59], v6 offset0:8 offset1:41
	global_store_dwordx4 v[60:61], v[50:53], off
	s_andn2_b64 vcc, exec, s[2:3]
	s_waitcnt lgkmcnt(0)
	v_cvt_pk_bf16_f32 v50, v58, v59
	ds_read2_b32 v[52:53], v6 offset0:74 offset1:107
	s_waitcnt lgkmcnt(0)
	v_cvt_pk_bf16_f32 v51, v52, v53
	ds_read2_b32 v[52:53], v6 offset0:140 offset1:173
	s_waitcnt lgkmcnt(0)
	v_cvt_pk_bf16_f32 v52, v52, v53
	ds_read2_b32 v[58:59], v6 offset0:206 offset1:239
	s_waitcnt lgkmcnt(0)
	v_cvt_pk_bf16_f32 v53, v58, v59
	v_add_u32_e32 v58, 8, v54
	v_ashrrev_i32_e32 v59, 31, v58
	v_lshlrev_b64 v[58:59], 12, v[58:59]
	ds_read2_b32 v[60:61], v6 offset0:16 offset1:49
	v_lshl_add_u64 v[58:59], v[56:57], 0, v[58:59]
	global_store_dwordx4 v[58:59], v[50:53], off
	s_waitcnt lgkmcnt(0)
	s_nop 0
	v_cvt_pk_bf16_f32 v50, v60, v61
	v_add_u32_e32 v60, 16, v54
	ds_read2_b32 v[52:53], v6 offset0:82 offset1:115
	v_ashrrev_i32_e32 v61, 31, v60
	s_waitcnt lgkmcnt(0)
	v_cvt_pk_bf16_f32 v51, v52, v53
	ds_read2_b32 v[52:53], v6 offset0:148 offset1:181
	v_lshlrev_b64 v[60:61], 12, v[60:61]
	v_add_u32_e32 v54, 24, v54
	s_waitcnt lgkmcnt(0)
	v_cvt_pk_bf16_f32 v52, v52, v53
	ds_read2_b32 v[58:59], v6 offset0:214 offset1:247
	s_waitcnt lgkmcnt(0)
	v_cvt_pk_bf16_f32 v53, v58, v59
	v_lshl_add_u64 v[60:61], v[56:57], 0, v[60:61]
	v_ashrrev_i32_e32 v55, 31, v54
	ds_read2_b32 v[58:59], v6 offset0:24 offset1:57
	global_store_dwordx4 v[60:61], v[50:53], off
	v_lshlrev_b64 v[54:55], 12, v[54:55]
	v_lshl_add_u64 v[54:55], v[56:57], 0, v[54:55]
	s_waitcnt lgkmcnt(0)
	v_cvt_pk_bf16_f32 v50, v58, v59
	ds_read2_b32 v[52:53], v6 offset0:90 offset1:123
	s_waitcnt lgkmcnt(0)
	v_cvt_pk_bf16_f32 v51, v52, v53
	ds_read2_b32 v[52:53], v6 offset0:156 offset1:189
	s_waitcnt lgkmcnt(0)
	v_cvt_pk_bf16_f32 v52, v52, v53
	ds_read2_b32 v[58:59], v6 offset0:222 offset1:255
	s_waitcnt lgkmcnt(0)
	v_cvt_pk_bf16_f32 v53, v58, v59
	global_store_dwordx4 v[54:55], v[50:53], off
	s_waitcnt lgkmcnt(0)
	s_cbranch_vccnz .Lt4_166
; #define LAS __attribute__((address_space(3)))
; __device__ __forceinline__ unsigned cvt_pk_bf16(float lo, float hi) { unsigned r; asm volatile("v_cvt_pk_bf16_f32 %0, %1, %2" : "=v"(r) : "v"(lo), "v"(hi)); return r; }
; __device__ __forceinline__ int item_d0(int n0, int mode) { if (mode != 1) return n0; const int up = n0 >= FF, jj = up ? n0 - FF : n0; return (jj >> 7) * 256 + up * 128 + (jj & 127); }
; #define SEAM(k) do { } while (0)
; #define SEAM(k) do { if (IN(k) && IN((k) + 1)) { if ((k) == 0) cg::this_grid().sync(); else xcd_barrier(xbar); } } while (0)
; template <int MODE>
; __device__ __forceinline__ void transpose_finish(const float (&r)[32], int K, int N, bf16_t* WT, LAS float* scr, int item, int lane) {
;     const int nblk = N / 32, kb = item / nblk, nb = item % nblk, k0 = 64 * kb, d0 = item_d0(32 * nb, MODE);
; #pragma unroll
;     for (int i = 0; i < 32; ++i) { const int kk = 2 * i + (lane >> 5); scr[kk * 33 + (lane & 31)] = r[i]; }
;     asm volatile("s_waitcnt lgkmcnt(0)" ::: "memory");
;     const int c = lane & 7;
; #pragma unroll
;     for (int j = 0; j < 4; ++j) { const int n = (lane >> 3) + 8 * j; const LAS float* sp = scr + (8 * c) * 33 + n;
;         u32x4 o; o.x = cvt_pk_bf16(sp[0 * 33], sp[1 * 33]); o.y = cvt_pk_bf16(sp[2 * 33], sp[3 * 33]); o.z = cvt_pk_bf16(sp[4 * 33], sp[5 * 33]); o.w = cvt_pk_bf16(sp[6 * 33], sp[7 * 33]);
;         *(u32x4*)(WT + (size_t)(d0 + n) * K + k0 + 8 * c) = o; }
;     asm volatile("s_waitcnt lgkmcnt(0)" ::: "memory");
; }
; __global__ void __launch_bounds__(512, 2) mk_fwd(Args args) {
;     ...
;     SEAM(4);
	ds_write2_b32 v10, v11, v12 offset1:66
	ds_write2_b32 v10, v13, v14 offset0:132 offset1:198
	ds_write2_b32 v43, v15, v16 offset0:8 offset1:74
	ds_write2_b32 v43, v17, v18 offset0:140 offset1:206
	ds_write2_b32 v44, v19, v20 offset0:16 offset1:82
	ds_write2_b32 v44, v21, v22 offset0:148 offset1:214
	ds_write2_b32 v45, v23, v24 offset0:24 offset1:90
	ds_write2_b32 v45, v25, v26 offset0:156 offset1:222
	ds_write2_b32 v46, v27, v28 offset0:32 offset1:98
	ds_write2_b32 v46, v29, v30 offset0:164 offset1:230
	ds_write2_b32 v47, v31, v32 offset0:40 offset1:106
	ds_write2_b32 v47, v33, v34 offset0:172 offset1:238
	ds_write2_b32 v48, v35, v36 offset0:48 offset1:114
	ds_write2_b32 v48, v37, v38 offset0:180 offset1:246
	ds_write2_b32 v49, v39, v40 offset0:56 offset1:122
	ds_write2_b32 v49, v41, v42 offset0:188 offset1:254
	s_ashr_i32 s0, s13, 31
	s_waitcnt lgkmcnt(0)
	s_lshr_b32 s0, s0, 26
	ds_read2_b32 v[44:45], v6 offset1:33
	s_add_i32 s0, s13, s0
	s_waitcnt lgkmcnt(0)
	v_cvt_pk_bf16_f32 v44, v44, v45
	ds_read2_b32 v[46:47], v6 offset0:66 offset1:99
	s_andn2_b32 s0, s0, 63
	s_waitcnt lgkmcnt(0)
	v_cvt_pk_bf16_f32 v45, v46, v47
	ds_read2_b32 v[46:47], v6 offset0:132 offset1:165
	s_sub_i32 s1, s13, s0
	s_waitcnt lgkmcnt(0)
	v_cvt_pk_bf16_f32 v46, v46, v47
	ds_read2_b32 v[48:49], v6 offset0:198 offset1:231
	s_lshl_b32 s2, s1, 5
	s_waitcnt lgkmcnt(0)
	v_cvt_pk_bf16_f32 v47, v48, v49
	v_or_b32_e32 v48, s2, v5
	s_ashr_i32 s1, s0, 31
	v_ashrrev_i32_e32 v49, 31, v48
	v_lshl_add_u64 v[50:51], s[0:1], 1, v[2:3]
	v_lshlrev_b64 v[48:49], 12, v[48:49]
	v_lshl_add_u64 v[48:49], v[50:51], 0, v[48:49]
	ds_read2_b32 v[52:53], v6 offset0:8 offset1:41
	global_store_dwordx4 v[48:49], v[44:47], off
	s_waitcnt lgkmcnt(0)
	s_nop 0
	v_cvt_pk_bf16_f32 v44, v52, v53
	ds_read2_b32 v[46:47], v6 offset0:74 offset1:107
	s_waitcnt lgkmcnt(0)
	v_cvt_pk_bf16_f32 v45, v46, v47
	ds_read2_b32 v[46:47], v6 offset0:140 offset1:173
	s_waitcnt lgkmcnt(0)
	v_cvt_pk_bf16_f32 v46, v46, v47
	ds_read2_b32 v[48:49], v6 offset0:206 offset1:239
	s_waitcnt lgkmcnt(0)
	v_cvt_pk_bf16_f32 v47, v48, v49
	v_or_b32_e32 v48, s2, v7
	v_ashrrev_i32_e32 v49, 31, v48
	v_lshlrev_b64 v[48:49], 12, v[48:49]
	ds_read2_b32 v[52:53], v6 offset0:16 offset1:49
	v_lshl_add_u64 v[48:49], v[50:51], 0, v[48:49]
	global_store_dwordx4 v[48:49], v[44:47], off
	s_waitcnt lgkmcnt(0)
	s_nop 0
	v_cvt_pk_bf16_f32 v44, v52, v53
	v_or_b32_e32 v52, s2, v8
	ds_read2_b32 v[46:47], v6 offset0:82 offset1:115
	v_ashrrev_i32_e32 v53, 31, v52
	s_waitcnt lgkmcnt(0)
	v_cvt_pk_bf16_f32 v45, v46, v47
	ds_read2_b32 v[46:47], v6 offset0:148 offset1:181
	v_lshlrev_b64 v[52:53], 12, v[52:53]
	s_waitcnt lgkmcnt(0)
	v_cvt_pk_bf16_f32 v46, v46, v47
	ds_read2_b32 v[48:49], v6 offset0:214 offset1:247
	s_waitcnt lgkmcnt(0)
	v_cvt_pk_bf16_f32 v47, v48, v49
	v_lshl_add_u64 v[52:53], v[50:51], 0, v[52:53]
	ds_read2_b32 v[48:49], v6 offset0:24 offset1:57
	global_store_dwordx4 v[52:53], v[44:47], off
	v_or_b32_e32 v52, s2, v9
	v_ashrrev_i32_e32 v53, 31, v52
	s_waitcnt lgkmcnt(0)
	v_cvt_pk_bf16_f32 v44, v48, v49
	ds_read2_b32 v[46:47], v6 offset0:90 offset1:123
	s_waitcnt lgkmcnt(0)
	v_cvt_pk_bf16_f32 v45, v46, v47
	ds_read2_b32 v[46:47], v6 offset0:156 offset1:189
	s_waitcnt lgkmcnt(0)
	v_cvt_pk_bf16_f32 v46, v46, v47
	ds_read2_b32 v[48:49], v6 offset0:222 offset1:255
	v_lshlrev_b64 v[52:53], 12, v[52:53]
	s_waitcnt lgkmcnt(0)
	v_cvt_pk_bf16_f32 v47, v48, v49
	v_lshl_add_u64 v[48:49], v[50:51], 0, v[52:53]
	global_store_dwordx4 v[48:49], v[44:47], off
	s_waitcnt lgkmcnt(0)
	s_branch .Lt4_166
.Ltail4_done:
	v_readlane_b32 s0, v239, 35
	v_readlane_b32 s1, v239, 36
	s_cmp_gt_i32 s1, 5
	s_cselect_b64 s[0:1], -1, 0
	s_and_b64 s[2:3], s[4:5], s[0:1]
	s_andn2_b64 vcc, exec, s[2:3]
	s_cbranch_vccnz .LBB0_445
	s_waitcnt vmcnt(0)
	s_waitcnt lgkmcnt(0)
	s_barrier
	s_mov_b64 s[2:3], exec
	v_readlane_b32 s4, v239, 21
	v_readlane_b32 s5, v239, 22
	s_and_b64 s[4:5], s[2:3], s[4:5]
	s_mov_b64 exec, s[4:5]
	s_cbranch_execz .LBB0_444
	s_add_i32 s4, 0, 0x22400
	v_mov_b32_e32 v0, s4
	s_waitcnt vmcnt(0) expcnt(0) lgkmcnt(0)
	ds_read_b32 v2, v0
	s_add_i32 s4, 0, 0x22404
	v_mov_b32_e32 v0, s4
	ds_read_b32 v0, v0
	s_waitcnt lgkmcnt(1)
	v_cmp_ne_u32_e32 vcc, 0, v2
	s_cbranch_vccnz .LBB0_408
	v_readlane_b32 s4, v239, 0
	v_readlane_b32 s5, v239, 1
	v_readlane_b32 s36, v239, 27
	s_load_dwordx2 s[8:9], s[4:5], 0x4
	v_readlane_b32 s42, v239, 33
	v_readlane_b32 s43, v239, 34
	s_add_u32 s4, s42, 0x48200
	s_addc_u32 s5, s43, 0
	s_add_u32 s6, s42, 0x48400
	s_addc_u32 s7, s43, 0
	s_waitcnt lgkmcnt(0)
	s_mul_i32 s33, s8, s97
	s_add_u32 s8, s42, 0x48500
	s_mul_i32 s33, s33, s9
	s_addc_u32 s9, s43, 0
	s_add_u32 s10, s42, 0x48600
	s_addc_u32 s11, s43, 0
	s_add_u32 s12, s42, 0x48700
	s_addc_u32 s13, s43, 0
	s_add_u32 s14, s42, 0x48800
	s_addc_u32 s15, s43, 0
	s_add_u32 s16, s42, 0x48900
	s_addc_u32 s17, s43, 0
	s_add_u32 s18, s42, 0x48a00
	s_addc_u32 s19, s43, 0
	s_add_u32 s20, s42, 0x48b00
	s_addc_u32 s21, s43, 0
	s_add_u32 s22, s42, 0x48c00
	s_addc_u32 s23, s43, 0
	s_add_u32 s24, s42, 0x48d00
	s_addc_u32 s25, s43, 0
	s_add_u32 s26, s42, 0x48e00
	s_addc_u32 s27, s43, 0
	s_add_u32 s28, s42, 0x48f00
	s_addc_u32 s29, s43, 0
	s_add_u32 s30, s42, 0x49000
	s_addc_u32 s31, s43, 0
	s_add_u32 s34, s42, 0x49100
	s_addc_u32 s35, s43, 0
	v_readlane_b32 s37, v239, 28
	s_add_u32 s36, s42, 0x49200
	v_readlane_b32 s38, v239, 29
	s_addc_u32 s37, s43, 0
	v_readlane_b32 s39, v239, 30
	s_add_u32 s38, s42, 0x49300
	s_addc_u32 s39, s43, 0
	s_mov_b32 s46, 1
	v_mov_b32_e32 v16, 0
	v_readlane_b32 s40, v239, 31
	v_readlane_b32 s41, v239, 32
	s_branch .LBB0_396
